# v10: GLA chunk segment-prefix loop unrolled (8 LDS reads issued together instead of 8 dependent round trips), on top of v9
# speedup vs baseline: 1.0104x; 1.0104x over previous
; #define LAS __attribute__((address_space(3)))
; __device__ __forceinline__ unsigned pk2(float lo, float hi) { f32x2 v = {lo, hi}; bf16x2_t b = __builtin_convertvector(v, bf16x2_t); return __builtin_bit_cast(unsigned, b); }
; __device__ __forceinline__ float bf_lo(unsigned u) { return __uint_as_float(u << 16); }
; __device__ __forceinline__ float bf_hi(unsigned u) { return __uint_as_float(u & 0xffff0000u); }
; __device__ __forceinline__ void gla_item(LAS unsigned char* lds, const bf16_t* __restrict__ GQ, const bf16_t* __restrict__ GK, const float* __restrict__ LA, ...
;     ...
;             f32x2 prefix = {0.f, 0.f}, total = {0.f, 0.f};
; #pragma unroll 4
;             for (int s = 0; s < 16; ++s) { const f32x2 v = segc[s * 32 + dp]; total += v; if (s < sg) prefix += v; }
;             f32x2 etot; etot.x = __expf(total.x); etot.y = __expf(total.y);
;             float kd0[4], kd1[4];
; #pragma unroll
;             for (int i = 0; i < 4; ++i) { const f32x2 cm = prefix + cum[i]; f32x2 ep, em; ep.x = __expf(cm.x); ep.y = __expf(cm.y);
;                 em.x = __builtin_amdgcn_rcpf(ep.x); em.y = __builtin_amdgcn_rcpf(ep.y);
;                 const float q0 = bf_lo(q_n[i]), q1 = bf_hi(q_n[i]), k0 = bf_lo(k_n[i]), k1 = bf_hi(k_n[i]);
;                 const int o = (4 * sg + i) * KP + dp * 4;
;                 *(LAS unsigned*)(lds + O_QF + o) = pk2(q0 * ep.x, q1 * ep.y);
;                 *(LAS unsigned*)(lds + O_QB + o) = pk2(q0 * em.x, q1 * em.y);
;                 *(LAS unsigned*)(lds + O_KF + o) = pk2(k0 * em.x, k1 * em.y);
;                 *(LAS unsigned*)(lds + O_KB + o) = pk2(k0 * ep.x, k1 * ep.y);
;                 kd0[i] = k0 * (etot.x * em.x); kd1[i] = k1 * (etot.y * em.y); }
.LBB0_381:
	v_cndmask_b32_e64 v18, 0, 1, s[84:85]
	s_mov_b32 s51, s50
	v_lshl_add_u32 v22, v18, 12, v128
	s_mov_b32 s48, 0
	v_mov_b32_e32 v18, 0
	v_mov_b32_e32 v19, v129
	v_mov_b32_e32 v20, 0
	v_mov_b32_e32 v21, v129
	v_add_u32_e32 v176, 0x800, v22
	ds_read2_b64 v[180:183], v22 offset1:32
	ds_read2_b64 v[184:187], v22 offset0:64 offset1:96
	ds_read2_b64 v[188:191], v22 offset0:128 offset1:160
	ds_read2_b64 v[192:195], v22 offset0:192 offset1:224
	ds_read2_b64 v[196:199], v176 offset1:32
	ds_read2_b64 v[200:203], v176 offset0:64 offset1:96
	ds_read2_b64 v[204:207], v176 offset0:128 offset1:160
	ds_read2_b64 v[208:211], v176 offset0:192 offset1:224
	s_waitcnt lgkmcnt(7)
	v_cmp_lt_i32_e32 vcc, 0, v103
	v_pk_add_f32 v[20:21], v[20:21], v[180:181]
	v_pk_add_f32 v[24:25], v[18:19], v[180:181]
	v_cndmask_b32_e32 v19, v19, v25, vcc
	v_cndmask_b32_e32 v18, v18, v24, vcc
	v_cmp_lt_i32_e32 vcc, 1, v103
	v_pk_add_f32 v[20:21], v[20:21], v[182:183]
	v_pk_add_f32 v[24:25], v[18:19], v[182:183]
	v_cndmask_b32_e32 v19, v19, v25, vcc
	v_cndmask_b32_e32 v18, v18, v24, vcc
	s_waitcnt lgkmcnt(6)
	v_cmp_lt_i32_e32 vcc, 2, v103
	v_pk_add_f32 v[20:21], v[20:21], v[184:185]
	v_pk_add_f32 v[24:25], v[18:19], v[184:185]
	v_cndmask_b32_e32 v19, v19, v25, vcc
	v_cndmask_b32_e32 v18, v18, v24, vcc
	v_cmp_lt_i32_e32 vcc, 3, v103
	v_pk_add_f32 v[20:21], v[20:21], v[186:187]
	v_pk_add_f32 v[24:25], v[18:19], v[186:187]
	v_cndmask_b32_e32 v19, v19, v25, vcc
	v_cndmask_b32_e32 v18, v18, v24, vcc
	s_waitcnt lgkmcnt(5)
	v_cmp_lt_i32_e32 vcc, 4, v103
	v_pk_add_f32 v[20:21], v[20:21], v[188:189]
	v_pk_add_f32 v[24:25], v[18:19], v[188:189]
	v_cndmask_b32_e32 v19, v19, v25, vcc
	v_cndmask_b32_e32 v18, v18, v24, vcc
	v_cmp_lt_i32_e32 vcc, 5, v103
	v_pk_add_f32 v[20:21], v[20:21], v[190:191]
	v_pk_add_f32 v[24:25], v[18:19], v[190:191]
	v_cndmask_b32_e32 v19, v19, v25, vcc
	v_cndmask_b32_e32 v18, v18, v24, vcc
	s_waitcnt lgkmcnt(4)
	v_cmp_lt_i32_e32 vcc, 6, v103
	v_pk_add_f32 v[20:21], v[20:21], v[192:193]
	v_pk_add_f32 v[24:25], v[18:19], v[192:193]
	v_cndmask_b32_e32 v19, v19, v25, vcc
	v_cndmask_b32_e32 v18, v18, v24, vcc
	v_cmp_lt_i32_e32 vcc, 7, v103
	v_pk_add_f32 v[20:21], v[20:21], v[194:195]
	v_pk_add_f32 v[24:25], v[18:19], v[194:195]
	v_cndmask_b32_e32 v19, v19, v25, vcc
	v_cndmask_b32_e32 v18, v18, v24, vcc
	s_waitcnt lgkmcnt(3)
	v_cmp_lt_i32_e32 vcc, 8, v103
	v_pk_add_f32 v[20:21], v[20:21], v[196:197]
	v_pk_add_f32 v[24:25], v[18:19], v[196:197]
	v_cndmask_b32_e32 v19, v19, v25, vcc
	v_cndmask_b32_e32 v18, v18, v24, vcc
	v_cmp_lt_i32_e32 vcc, 9, v103
	v_pk_add_f32 v[20:21], v[20:21], v[198:199]
	v_pk_add_f32 v[24:25], v[18:19], v[198:199]
	v_cndmask_b32_e32 v19, v19, v25, vcc
	v_cndmask_b32_e32 v18, v18, v24, vcc
	s_waitcnt lgkmcnt(2)
	v_cmp_lt_i32_e32 vcc, 10, v103
	v_pk_add_f32 v[20:21], v[20:21], v[200:201]
	v_pk_add_f32 v[24:25], v[18:19], v[200:201]
	v_cndmask_b32_e32 v19, v19, v25, vcc
	v_cndmask_b32_e32 v18, v18, v24, vcc
	v_cmp_lt_i32_e32 vcc, 11, v103
	v_pk_add_f32 v[20:21], v[20:21], v[202:203]
	v_pk_add_f32 v[24:25], v[18:19], v[202:203]
	v_cndmask_b32_e32 v19, v19, v25, vcc
	v_cndmask_b32_e32 v18, v18, v24, vcc
	s_waitcnt lgkmcnt(1)
	v_cmp_lt_i32_e32 vcc, 12, v103
	v_pk_add_f32 v[20:21], v[20:21], v[204:205]
	v_pk_add_f32 v[24:25], v[18:19], v[204:205]
	v_cndmask_b32_e32 v19, v19, v25, vcc
	v_cndmask_b32_e32 v18, v18, v24, vcc
	v_cmp_lt_i32_e32 vcc, 13, v103
	v_pk_add_f32 v[20:21], v[20:21], v[206:207]
	v_pk_add_f32 v[24:25], v[18:19], v[206:207]
	v_cndmask_b32_e32 v19, v19, v25, vcc
	v_cndmask_b32_e32 v18, v18, v24, vcc
	s_waitcnt lgkmcnt(0)
	v_cmp_lt_i32_e32 vcc, 14, v103
	v_pk_add_f32 v[20:21], v[20:21], v[208:209]
	v_pk_add_f32 v[24:25], v[18:19], v[208:209]
	v_cndmask_b32_e32 v19, v19, v25, vcc
	v_cndmask_b32_e32 v18, v18, v24, vcc
	v_cmp_lt_i32_e32 vcc, 15, v103
	v_pk_add_f32 v[20:21], v[20:21], v[210:211]
	v_pk_add_f32 v[24:25], v[18:19], v[210:211]
	v_cndmask_b32_e32 v19, v19, v25, vcc
	v_cndmask_b32_e32 v18, v18, v24, vcc
	v_pk_add_f32 v[16:17], v[16:17], v[18:19]
	s_waitcnt vmcnt(19)
	v_lshlrev_b32_e32 v28, 16, v120
	v_mul_f32_e32 v16, 0x3fb8aa3b, v16
	v_exp_f32_e32 v22, v16
	v_mul_f32_e32 v16, 0x3fb8aa3b, v17
	v_exp_f32_e32 v23, v16
	v_and_b32_e32 v29, 0xffff0000, v120
	v_rcp_f32_e32 v24, v22
	s_waitcnt vmcnt(18)
	v_lshlrev_b32_e32 v26, 16, v121
	v_rcp_f32_e32 v25, v23
	v_and_b32_e32 v27, 0xffff0000, v121
	v_pk_mul_f32 v[30:31], v[22:23], v[28:29]
	v_mul_f32_e32 v16, 0x3fb8aa3b, v21
	v_pk_mul_f32 v[28:29], v[24:25], v[28:29]
	v_pk_mul_f32 v[22:23], v[22:23], v[26:27]
	v_cvt_pk_bf16_f32 v21, v28, v29
	v_pk_mul_f32 v[28:29], v[24:25], v[26:27]
	v_cvt_pk_bf16_f32 v37, v22, v23
	v_cvt_pk_bf16_f32 v36, v28, v29
	v_pk_add_f32 v[28:29], v[44:45], v[18:19]
	s_waitcnt vmcnt(17)
	v_lshlrev_b32_e32 v32, 16, v118
	v_mul_f32_e32 v28, 0x3fb8aa3b, v28
	v_mul_f32_e32 v29, 0x3fb8aa3b, v29
	v_exp_f32_e32 v28, v28
	v_exp_f32_e32 v29, v29
	v_and_b32_e32 v33, 0xffff0000, v118
	v_exp_f32_e32 v16, v16
	v_rcp_f32_e32 v22, v28
	v_rcp_f32_e32 v23, v29
	v_pk_mul_f32 v[34:35], v[28:29], v[32:33]
	v_cvt_pk_bf16_f32 v17, v30, v31
	s_waitcnt vmcnt(16)
; __device__ __forceinline__ void gla_item(LAS unsigned char* lds, const bf16_t* __restrict__ GQ, const bf16_t* __restrict__ GK, const float* __restrict__ LA, ...
;     ...
;             for (int i = 0; i < 4; ++i) { const f32x2 cm = prefix + cum[i]; f32x2 ep, em; ep.x = __expf(cm.x); ep.y = __expf(cm.y);
;                 em.x = __builtin_amdgcn_rcpf(ep.x); em.y = __builtin_amdgcn_rcpf(ep.y);
;                 const float q0 = bf_lo(q_n[i]), q1 = bf_hi(q_n[i]), k0 = bf_lo(k_n[i]), k1 = bf_hi(k_n[i]);
;                 const int o = (4 * sg + i) * KP + dp * 4;
;                 *(LAS unsigned*)(lds + O_QF + o) = pk2(q0 * ep.x, q1 * ep.y);
;                 *(LAS unsigned*)(lds + O_QB + o) = pk2(q0 * em.x, q1 * em.y);
;                 *(LAS unsigned*)(lds + O_KF + o) = pk2(k0 * em.x, k1 * em.y);
;                 *(LAS unsigned*)(lds + O_KB + o) = pk2(k0 * ep.x, k1 * ep.y);
;                 kd0[i] = k0 * (etot.x * em.x); kd1[i] = k1 * (etot.y * em.y); }
;             u32x2 w0, w1; w0.x = pk2(kd0[0], kd0[1]); w0.y = pk2(kd0[2], kd0[3]); w1.x = pk2(kd1[0], kd1[1]); w1.y = pk2(kd1[2], kd1[3]);
;             *(LAS u32x2*)(lds + O_KDT + (2 * dp) * KP + sg * 8) = w0;
;             *(LAS u32x2*)(lds + O_KDT + (2 * dp + 1) * KP + sg * 8) = w1;
;             if (sg == 0) { dec[2 * dp] = etot.x; dec[2 * dp + 1] = etot.y; }
; #pragma unroll
;             for (int j = 0; j < 2; ++j) { const int c = tid + 512 * j; const int ch = c & 7; LAS unsigned char* vp = lds + O_VT + (c >> 3) * KP + ((ch >> 1) * 16 + (ch & 1) * 4) * 2;
;                 u32x2 lo, hi; lo.x = v_n[j].x; lo.y = v_n[j].y; hi.x = v_n[j].z; hi.y = v_n[j].w; *(LAS u32x2*)vp = lo; *(LAS u32x2*)(vp + 16) = hi; }
;             { const int n1 = (n + 1 < SEQ / 64) ? n + 1 : n;
; #pragma unroll
;               for (int i = 0; i < 4; ++i) { const size_t o1 = rbase + (size_t)n1 * 64 * 256 + i * 256; q_n[i] = *(const unsigned*)(GQ + o1); k_n[i] = *(const unsigned*)(GK + o1); }
; #pragma unroll
;               for (int j = 0; j < 2; ++j) v_n[j] = *(const u32x4*)(vbase0 + (size_t)j * 64 * SEQ + 64 * n1); }
;         }
;         __syncthreads();
;         if (wid < 4) {
;             const int ltile = (wid == 1 || wid == 2) ? 1 : 0, mtile = (wid == 1 || wid == 3) ? 1 : 0;
;             const bool needf = (wid != 3), needb = (wid != 2);
;             f32x16 af, ab;
; #pragma unroll
	v_lshlrev_b32_e32 v30, 16, v119
	v_and_b32_e32 v31, 0xffff0000, v119
	v_cvt_pk_bf16_f32 v34, v34, v35
	v_pk_mul_f32 v[32:33], v[22:23], v[32:33]
	ds_write2_b32 v130, v17, v34 offset1:36
	v_cvt_pk_bf16_f32 v17, v32, v33
	v_add_u32_e32 v38, 0x2400, v130
	v_pk_mul_f32 v[32:33], v[22:23], v[30:31]
	ds_write2_b32 v38, v21, v17 offset1:36
	v_cvt_pk_bf16_f32 v17, v32, v33
	v_add_u32_e32 v21, 0x4800, v130
	v_pk_mul_f32 v[28:29], v[28:29], v[30:31]
	ds_write2_b32 v21, v36, v17 offset1:36
	v_cvt_pk_bf16_f32 v17, v28, v29
	v_add_u32_e32 v39, 0x6c00, v130
	v_mov_b32_e32 v28, v24
	v_mov_b32_e32 v29, v22
	v_mov_b32_e32 v22, v25
	v_pk_add_f32 v[24:25], v[42:43], v[18:19]
	v_mul_f32_e32 v20, 0x3fb8aa3b, v20
	ds_write2_b32 v39, v37, v17 offset1:36
	v_pk_mul_f32 v[22:23], v[16:17], v[22:23] op_sel_hi:[0,1]
	v_mul_f32_e32 v17, 0x3fb8aa3b, v24
	v_exp_f32_e32 v20, v20
	v_exp_f32_e32 v24, v17
	v_mul_f32_e32 v17, 0x3fb8aa3b, v25
	v_exp_f32_e32 v25, v17
	v_pk_add_f32 v[18:19], v[40:41], v[18:19]
	v_pk_mul_f32 v[28:29], v[20:21], v[28:29] op_sel_hi:[0,1]
	v_mul_f32_e32 v18, 0x3fb8aa3b, v18
	v_mul_f32_e32 v19, 0x3fb8aa3b, v19
	v_exp_f32_e32 v18, v18
	v_exp_f32_e32 v19, v19
	v_mov_b32_e32 v32, v26
	v_mov_b32_e32 v33, v30
	v_mov_b32_e32 v30, v27
	v_pk_mul_f32 v[28:29], v[28:29], v[32:33]
	v_pk_mul_f32 v[22:23], v[22:23], v[30:31]
	v_rcp_f32_e32 v26, v24
	v_rcp_f32_e32 v27, v25
	s_waitcnt vmcnt(14)
	v_lshlrev_b32_e32 v30, 16, v115
	v_and_b32_e32 v31, 0xffff0000, v115
	v_lshlrev_b32_e32 v32, 16, v113
	v_and_b32_e32 v33, 0xffff0000, v113
	v_pk_mul_f32 v[34:35], v[24:25], v[32:33]
	v_pk_mul_f32 v[24:25], v[24:25], v[30:31]
	v_cvt_pk_bf16_f32 v17, v34, v35
	v_cvt_pk_bf16_f32 v40, v24, v25
	v_rcp_f32_e32 v24, v18
	v_rcp_f32_e32 v25, v19
	v_pk_mul_f32 v[32:33], v[26:27], v[32:33]
	s_waitcnt vmcnt(12)
	v_lshlrev_b32_e32 v34, 16, v112
	v_and_b32_e32 v35, 0xffff0000, v112
	v_cvt_pk_bf16_f32 v42, v32, v33
	v_pk_mul_f32 v[32:33], v[26:27], v[30:31]
	v_pk_mul_f32 v[36:37], v[18:19], v[34:35]
	v_cvt_pk_bf16_f32 v43, v32, v33
	v_lshlrev_b32_e32 v32, 16, v114
	v_and_b32_e32 v33, 0xffff0000, v114
	v_cvt_pk_bf16_f32 v36, v36, v37
	v_pk_mul_f32 v[34:35], v[24:25], v[34:35]
	ds_write2_b32 v130, v17, v36 offset0:72 offset1:108
	v_cvt_pk_bf16_f32 v17, v34, v35
	v_pk_mul_f32 v[34:35], v[24:25], v[32:33]
	ds_write2_b32 v38, v42, v17 offset0:72 offset1:108
	v_cvt_pk_bf16_f32 v17, v34, v35
	v_pk_mul_f32 v[18:19], v[18:19], v[32:33]
	ds_write2_b32 v21, v43, v17 offset0:72 offset1:108
	v_cvt_pk_bf16_f32 v17, v18, v19
	v_mov_b32_e32 v18, v26
	v_mov_b32_e32 v19, v24
	v_pk_mul_f32 v[18:19], v[20:21], v[18:19] op_sel_hi:[0,1]
	v_mov_b32_e32 v34, v30
	v_mov_b32_e32 v35, v32
	v_mov_b32_e32 v24, v27
	v_pk_mul_f32 v[18:19], v[18:19], v[34:35]
	v_pk_mul_f32 v[24:25], v[16:17], v[24:25] op_sel_hi:[0,1]
	v_mov_b32_e32 v32, v31
	v_pk_mul_f32 v[24:25], v[24:25], v[32:33]
	v_cvt_pk_bf16_f32 v26, v28, v29
	v_cvt_pk_bf16_f32 v27, v18, v19
	ds_write2_b32 v39, v40, v17 offset0:72 offset1:108
	v_cvt_pk_bf16_f32 v18, v22, v23
	v_cvt_pk_bf16_f32 v19, v24, v25
	ds_write_b64 v131, v[26:27] offset:36864
	ds_write_b64 v132, v[18:19] offset:36864
	s_and_saveexec_b64 s[86:87], s[0:1]
	v_mov_b32_e32 v21, v16
	ds_write_b64 v110, v[20:21]
	s_or_b64 exec, exec, s[86:87]
	s_add_i32 s50, s51, 1
	s_cmp_lg_u32 s51, 63
	s_cselect_b32 s56, s50, 63
	s_lshl_b32 s48, s56, 14
	v_lshl_add_u64 v[16:17], v[80:81], 0, s[48:49]
	s_lshl_b32 s48, s56, 15
	s_waitcnt vmcnt(7)
	ds_write2_b64 v136, v[56:57], v[58:59] offset0:128 offset1:130
	s_waitcnt vmcnt(5)
	ds_write2_b64 v137, v[60:61], v[62:63] offset0:128 offset1:130
	v_lshl_add_u64 v[18:19], v[88:89], 0, s[48:49]
	v_lshl_add_u64 v[20:21], v[90:91], 0, s[48:49]
	v_lshlrev_b64 v[16:17], 1, v[16:17]
	s_mov_b64 s[58:59], 0x400
	global_load_dword v120, v[18:19], off
	global_load_dword v121, v[20:21], off
	global_load_dword v118, v[18:19], off offset:512
	global_load_dword v119, v[20:21], off offset:512
	v_lshl_add_u64 v[18:19], v[16:17], 0, s[58:59]
	s_mov_b64 s[58:59], 0x600
	v_lshl_add_u64 v[20:21], s[66:67], 0, v[18:19]
	v_lshl_add_u64 v[18:19], s[68:69], 0, v[18:19]
	v_lshl_add_u64 v[16:17], v[16:17], 0, s[58:59]
	global_load_dword v115, v[18:19], off
	v_lshl_add_u64 v[18:19], s[66:67], 0, v[16:17]
	v_lshl_add_u64 v[16:17], s[68:69], 0, v[16:17]
	s_lshl_b32 s48, s56, 7
	global_load_dword v112, v[18:19], off
	global_load_dword v114, v[16:17], off
	v_lshl_add_u64 v[16:17], v[86:87], 0, s[48:49]
	global_load_dword v113, v[20:21], off
	global_load_dwordx4 v[56:59], v[16:17], off
	v_add_co_u32_e32 v16, vcc, 0x80000, v16
	s_nop 1
	v_addc_co_u32_e32 v17, vcc, 0, v17, vcc
	global_load_dwordx4 v[60:63], v[16:17], off
	s_andn2_b64 vcc, exec, s[78:79]
	s_waitcnt lgkmcnt(0)
	s_barrier
	s_cbranch_vccnz .LBB0_391
	v_mov_b32_e32 v16, 0
	s_andn2_b64 vcc, exec, s[80:81]
	v_mov_b32_e32 v32, 0
	v_mov_b32_e32 v33, 0
	v_mov_b32_e32 v34, 0
	v_mov_b32_e32 v35, 0
	v_mov_b32_e32 v36, 0
	v_mov_b32_e32 v37, 0
	v_mov_b32_e32 v38, 0
	v_mov_b32_e32 v39, 0
	v_mov_b32_e32 v40, 0
	v_mov_b32_e32 v41, 0
	v_mov_b32_e32 v42, 0
	v_mov_b32_e32 v43, 0
	v_mov_b32_e32 v44, 0
	v_mov_b32_e32 v45, 0
	v_mov_b32_e32 v46, 0
	v_mov_b32_e32 v47, 0
	s_cbranch_vccnz .LBB0_388
	ds_read_b128 v[18:21], v138 offset:18432
	ds_read_b128 v[22:25], v139
	s_waitcnt lgkmcnt(0)
	v_mfma_f32_32x32x16_bf16 v[32:47], v[18:21], v[22:25], 0
	ds_read_b128 v[18:21], v138 offset:18464
	ds_read_b128 v[22:25], v139 offset:32
	s_waitcnt lgkmcnt(0)
	v_mfma_f32_32x32x16_bf16 v[32:47], v[18:21], v[22:25], v[32:47]
	ds_read_b128 v[18:21], v138 offset:18496
	ds_read_b128 v[22:25], v139 offset:64
	s_waitcnt lgkmcnt(0)
	v_mfma_f32_32x32x16_bf16 v[32:47], v[18:21], v[22:25], v[32:47]
	ds_read_b128 v[18:21], v138 offset:18528
	ds_read_b128 v[22:25], v139 offset:96
	s_waitcnt lgkmcnt(0)
	v_mfma_f32_32x32x16_bf16 v[32:47], v[18:21], v[22:25], v[32:47]
